# speedup vs baseline: 1.0239x; 1.0039x over previous
; DEVI int opq_tid() { int t = threadIdx.x; asm volatile("" : "+v"(t)); return t; }
; #define WAIT_V0() asm volatile("s_waitcnt vmcnt(0)" ::: "memory")
; DEVI int v_st(int k, int c) { const int kk = (k & ~0xC) | ((k & 4) << 1) | ((k & 8) >> 1); return ((kk >> 3) * 4 + (c >> 5)) * 512 + ((kk & 7) * 32 + (c & 31)) * 2; }
; DEVI int v_rd_base(int lane) { return ((lane & 3) << 3) | (((lane >> 2) & 3) << 6) | (((lane >> 4) & 1) << 5) | (((lane >> 5) & 1) << 8); }
; DEVI void attn_item(const u16* __restrict__ Qb, const u16* __restrict__ Kn, const u16* __restrict__ Kr, const u16* __restrict__ Vh, u16* __restrict__ Ob, int seq) {
;   const int tid = opq_tid(), wid = tid >> 6, lane = tid & 63, r32 = lane & 31, hi = lane >> 5;
;   char* V_lds = g_shm; char* K_lds = g_shm + 2 * SHM_V;
;   float* wsl = (float*)(g_shm + 2 * SHM_V + 2 * SHM_K) + wid * 64; float* li_l = wsl; float* al_l = wsl + 32;
;   float m_reg = -1e30f, l_reg = 0.f;
;   f32x16 o[4];
; #pragma unroll
;   for (int d = 0; d < 4; ++d)
; #pragma unroll
;     for (int r = 0; r < 16; ++r) o[d][r] = 0.f;
;   bf16x8 qr[12];
;   const u16* Qw = Qb + (long)(wid * 32 + r32) * 1536 + hi * 8;
; #pragma unroll
;   for (int d0 = 0; d0 < 12; ++d0) qr[d0] = *(const bf16x8*)(Qw + d0 * 16);
;   const int krow = tid >> 3, c8 = tid & 7;
;   const u16* knp = Kn + (long)krow * 2048 + c8 * 8;
;   const u16* krp = Kr + (long)krow * 768 + c8 * 8;
;   const int kwr = krow * KROW + c8 * 16;
;   const int sr = tid >> 4, sc = (tid & 15) * 8, vst0 = v_st(sr, sc), vst1 = v_st(32 + sr, sc);
;   const u16* vp = Vh + (long)sr * 2048 + sc;
;   const int vb0 = (int)(uintptr_t)V_lds + v_rd_base(lane);
;   bf16x8 ks[3], vs0, vs1;
;     ...
;   const int NTk = seq / 64;
;   SLOAD(0); WAIT_V0(); SWRITE(0); __syncthreads();
; DEVI void mla_attn(const Params& P, int g) {
;     ...
;   for (int it0 = blockIdx.x; it0 < nitems; it0 += gridDim.x) {
;     int it = it0;
;     { const int nb = gridDim.x;
;       if ((nb & 7) == 0) { const int w = it0 / nb, b = it0 - w * nb; if ((w + 1) * nb <= nitems) it = w * nb + (b & 7) * (nb >> 3) + (b >> 3); } }
;     const int qb = it % nqb, hh = (it / nqb) & 7, sq = it / (nqb * 8);
;     const long r0 = (long)sq * S;
;     attn_item(q + (r0 + qb * 256) * 1536 + hh * 192, kv + r0 * 2048 + hh * 256, down + r0 * 768 + 640, kv + r0 * 2048 + hh * 256 + 128,
;               o + (r0 + qb * 256) * 1024 + hh * 128, S);
.LBB0_1259:
	s_abs_i32 s6, s2
	s_mul_hi_u32 s7, s6, s33
	s_mul_i32 s10, s7, s15
	s_sub_i32 s10, s6, s10
	s_ashr_i32 s3, s2, 31
	s_add_i32 s11, s7, 1
	s_sub_i32 s12, s10, s15
	s_cmp_ge_u32 s10, s15
	s_cselect_b32 s7, s11, s7
	s_cselect_b32 s10, s12, s10
	s_add_i32 s11, s7, 1
	s_cmp_ge_u32 s10, s15
	s_cselect_b32 s7, s11, s7
	s_xor_b32 s7, s7, s3
	s_sub_i32 s7, s7, s3
	s_mul_i32 s10, s7, s15
	s_sub_i32 s10, s2, s10
	s_mul_hi_u32 s2, s6, s68
	s_and_b32 s40, s7, 7
	s_mul_i32 s7, s2, s21
	s_sub_i32 s6, s6, s7
	s_add_i32 s7, s2, 1
	s_sub_i32 s11, s6, s21
	s_cmp_ge_u32 s6, s21
	s_cselect_b32 s2, s7, s2
	s_cselect_b32 s6, s11, s6
	s_add_i32 s7, s2, 1
	s_cmp_ge_u32 s6, s21
	s_cselect_b32 s2, s7, s2
	s_xor_b32 s2, s2, s3
	s_sub_i32 s2, s2, s3
	s_ashr_i32 s3, s2, 31
	s_lshl_b64 s[12:13], s[2:3], s31
	s_lshl_b32 s2, s10, 8
	s_ashr_i32 s3, s2, 31
	s_add_u32 s6, s12, s2
	s_addc_u32 s7, s13, s3
	s_mul_i32 s2, s7, 0xc00
	s_mul_hi_u32 s3, s6, 0xc00
	s_add_i32 s3, s3, s2
	s_mul_i32 s2, s6, 0xc00
	v_readlane_b32 s10, v253, 48
	s_add_u32 s2, s10, s2
	v_readlane_b32 s10, v253, 49
	s_addc_u32 s3, s10, s3
	s_mul_i32 s10, s40, 0x180
	s_add_u32 s10, s2, s10
	s_addc_u32 s11, s3, 0
	s_lshl_b64 s[2:3], s[12:13], 12
	v_readlane_b32 s41, v253, 50
	s_add_u32 s41, s41, s2
	v_readlane_b32 s42, v253, 51
	s_addc_u32 s43, s42, s3
	s_lshl_b32 s48, s40, 9
	v_mov_b32_e32 v34, v167
	s_add_u32 s42, s41, s48
	s_mulk_i32 s13, 0x600
	s_mul_hi_u32 s41, s12, 0x600
	s_addc_u32 s43, s43, 0
	v_ashrrev_i32_e32 v22, 3, v34
	s_add_i32 s49, s41, s13
	s_mul_i32 s58, s12, 0x600
	v_ashrrev_i32_e32 v23, 31, v22
	s_add_u32 s12, s17, s58
	v_lshlrev_b64 v[24:25], 12, v[22:23]
	v_lshlrev_b32_e32 v23, 4, v34
	s_addc_u32 s13, s18, s49
	v_lshl_add_u64 v[2:3], s[42:43], 0, v[24:25]
	v_and_b32_e32 v26, 0x70, v23
	v_mov_b32_e32 v27, v1
	v_lshl_add_u64 v[6:7], v[2:3], 0, v[26:27]
	v_mov_b64_e32 v[2:3], s[12:13]
	s_movk_i32 s64, 0x600
	v_ashrrev_i32_e32 v28, 4, v34
	v_mad_i64_i32 v[2:3], s[12:13], v22, s64, v[2:3]
	v_lshlrev_b32_e32 v35, 3, v34
	v_ashrrev_i32_e32 v29, 31, v28
	v_lshl_add_u64 v[10:11], v[2:3], 0, v[26:27]
	v_and_b32_e32 v0, 0x78, v35
	v_lshlrev_b64 v[30:31], 12, v[28:29]
	s_mov_b32 s12, 0x16500000
	v_lshl_add_u64 v[2:3], s[42:43], 0, v[30:31]
	v_lshlrev_b32_e32 v4, 1, v0
	v_mov_b32_e32 v5, v1
	v_add_co_u32_e32 v10, vcc, s12, v10
	v_lshl_add_u64 v[18:19], v[2:3], 0, v[4:5]
	s_nop 0
	v_addc_co_u32_e32 v11, vcc, 0, v11, vcc
	s_mov_b32 s12, 0x20000
	global_load_dwordx4 v[2:5], v[6:7], off
	s_nop 0
	global_load_dwordx4 v[6:9], v[6:7], off offset:128
	s_nop 0
	global_load_dwordx4 v[10:13], v[10:11], off offset:1280
	s_nop 0
	global_load_dwordx4 v[14:17], v[18:19], off offset:256
	v_add_co_u32_e32 v18, vcc, s12, v18
	v_ashrrev_i32_e32 v29, 1, v34
	s_movk_i32 s12, 0xffe0
	v_bfe_u32 v213, v34, 5, 1
	v_bfi_b32 v0, s12, v29, v34
	v_mov_b64_e32 v[32:33], s[10:11]
	v_mad_i64_i32 v[32:33], s[10:11], v0, s63, v[32:33]
	v_lshlrev_b32_e32 v0, 4, v213
	v_addc_co_u32_e32 v19, vcc, 0, v19, vcc
	v_lshl_add_u64 v[32:33], v[32:33], 0, v[0:1]
	global_load_dwordx4 v[18:21], v[18:19], off offset:256
	s_nop 0
	global_load_dwordx4 v[142:145], v[32:33], off
	global_load_dwordx4 v[138:141], v[32:33], off offset:32
	global_load_dwordx4 v[134:137], v[32:33], off offset:64
	global_load_dwordx4 v[130:133], v[32:33], off offset:96
	global_load_dwordx4 v[126:129], v[32:33], off offset:128
	global_load_dwordx4 v[122:125], v[32:33], off offset:160
	global_load_dwordx4 v[118:121], v[32:33], off offset:192
	global_load_dwordx4 v[114:117], v[32:33], off offset:224
	global_load_dwordx4 v[110:113], v[32:33], off offset:256
	global_load_dwordx4 v[106:109], v[32:33], off offset:288
	global_load_dwordx4 v[102:105], v[32:33], off offset:320
	global_load_dwordx4 v[98:101], v[32:33], off offset:352
	v_and_b32_e32 v170, 0xffffffe0, v29
	v_and_b32_e32 v29, 0xfffff0, v28
	v_lshlrev_b32_e32 v33, 1, v28
	v_and_or_b32 v29, v33, 8, v29
	v_lshrrev_b32_e32 v33, 1, v28
	v_lshrrev_b32_e32 v29, 1, v29
	v_bfe_u32 v36, v35, 5, 2
	v_and_b32_e32 v37, 3, v28
	v_or_b32_e32 v29, v29, v36
	v_and_or_b32 v33, v33, 4, v37
	v_lshlrev_b32_e32 v29, 9, v29
	v_lshlrev_b32_e32 v33, 6, v33
	v_and_b32_e32 v37, 48, v23
	v_add_u32_e32 v28, 32, v28
	v_or3_b32 v216, v29, v33, v37
	v_and_b32_e32 v29, 0xfffff0, v28
	v_lshlrev_b32_e32 v28, 1, v28
	v_and_or_b32 v28, v28, 8, v29
	v_lshrrev_b32_e32 v28, 1, v28
	v_or_b32_e32 v28, v28, v36
	v_lshlrev_b32_e32 v28, 9, v28
	v_mad_u64_u32 v[172:173], s[10:11], v22, s65, v[26:27]
	v_or3_b32 v217, v28, v33, v37
	s_waitcnt vmcnt(0)
	s_waitcnt vmcnt(16)
	ds_write_b128 v172, v[2:5] offset:32768
	s_waitcnt vmcnt(15)
	ds_write_b128 v172, v[6:9] offset:32896
	s_waitcnt vmcnt(14)
	ds_write_b128 v172, v[10:13] offset:33024
	s_waitcnt vmcnt(13)
	ds_write_b128 v216, v[14:17]
	s_waitcnt vmcnt(12)
	ds_write_b128 v217, v[18:21]
	v_lshlrev_b32_e32 v2, 1, v34
	v_and_b32_e32 v2, 32, v2
	s_movk_i32 s10, 0x118
	v_and_or_b32 v2, v35, s10, v2
	s_movk_i32 s12, 0xc0
	v_and_or_b32 v214, v23, s12, v2
	v_and_b32_e32 v2, 15, v34
	s_add_u32 s12, s8, s58
	v_lshl_add_u64 v[174:175], s[2:3], 0, v[30:31]
	v_lshlrev_b32_e32 v2, 4, v2
	s_addc_u32 s13, s9, s49
	v_and_b32_e32 v32, 0x3fffffc0, v34
	v_or3_b32 v174, v174, s48, v2
	v_mov_b64_e32 v[2:3], s[12:13]
	v_lshl_add_u32 v171, v32, 2, v212
	v_and_b32_e32 v32, 63, v34
	v_mad_i64_i32 v[2:3], s[12:13], v22, s64, v[2:3]
	v_lshl_add_u64 v[178:179], s[2:3], 0, v[24:25]
	v_mov_b32_e32 v16, v1
	v_mov_b32_e32 v17, v1
	v_and_b32_e32 v169, 31, v34
	v_cmp_gt_u32_e64 s[10:11], 32, v32
	v_lshl_add_u64 v[176:177], v[2:3], 0, v[26:27]
	v_or3_b32 v178, v178, s48, v26
	v_mov_b32_e32 v2, v1
	v_mov_b32_e32 v3, v1
	v_mov_b32_e32 v4, v1
	v_mov_b32_e32 v5, v1
	v_mov_b32_e32 v6, v1
	v_mov_b32_e32 v7, v1
	v_mov_b32_e32 v8, v1
	v_mov_b32_e32 v9, v1
	v_mov_b32_e32 v10, v1
	v_mov_b32_e32 v11, v1
	v_mov_b32_e32 v12, v1
	v_mov_b32_e32 v13, v1
	v_mov_b32_e32 v14, v1
	v_mov_b32_e32 v15, v1
	v_mov_b64_e32 v[64:65], v[16:17]
	v_mov_b64_e32 v[48:49], v[16:17]
	v_mov_b64_e32 v[32:33], v[16:17]
	s_mov_b32 s41, 0
	v_mul_u32_u24_e32 v218, 0x190, v169
	v_lshl_or_b32 v173, v169, 2, v171
	v_mad_u32_u24 v219, v169, s65, v0
	v_mov_b32_e32 v221, 0
	v_mov_b32_e32 v215, 0xf149f2ca
	v_mov_b64_e32 v[62:63], v[14:15]
	v_mov_b64_e32 v[60:61], v[12:13]
	v_mov_b64_e32 v[58:59], v[10:11]
	v_mov_b64_e32 v[56:57], v[8:9]
	v_mov_b64_e32 v[54:55], v[6:7]
	v_mov_b64_e32 v[52:53], v[4:5]
	v_mov_b64_e32 v[50:51], v[2:3]
	v_mov_b64_e32 v[46:47], v[14:15]
	v_mov_b64_e32 v[44:45], v[12:13]
	v_mov_b64_e32 v[42:43], v[10:11]
	v_mov_b64_e32 v[40:41], v[8:9]
	v_mov_b64_e32 v[38:39], v[6:7]
	v_mov_b64_e32 v[36:37], v[4:5]
	v_mov_b64_e32 v[34:35], v[2:3]
	v_mov_b64_e32 v[30:31], v[14:15]
	v_mov_b64_e32 v[28:29], v[12:13]
	v_mov_b64_e32 v[26:27], v[10:11]
	v_mov_b64_e32 v[24:25], v[8:9]
	v_mov_b64_e32 v[22:23], v[6:7]
	v_mov_b64_e32 v[20:21], v[4:5]
	v_mov_b64_e32 v[18:19], v[2:3]
	s_waitcnt lgkmcnt(0)
	s_barrier
; #define SLOAD(k0) do { ks[0] = *(const bf16x8*)(knp + (long)(k0) * 2048); ks[1] = *(const bf16x8*)(knp + (long)(k0) * 2048 + 64);          \
;     ks[2] = *(const bf16x8*)(krp + (long)(k0) * 768);                                                                           \
;     vs0 = *(const bf16x8*)(vp + (long)(k0) * 2048); vs1 = *(const bf16x8*)(vp + (long)((k0) + 32) * 2048); } while (0)
; DEVI void attn_item(const u16* __restrict__ Qb, const u16* __restrict__ Kn, const u16* __restrict__ Kr, const u16* __restrict__ Vh, u16* __restrict__ Ob, int seq) {
;     ...
;   for (int j = 0; j < NTk; ++j) {
;     const int cur = j & 1;
;     if (j + 1 < NTk) SLOAD((j + 1) * 64);
;     f32x16 p0, p1;
; #pragma unroll
;     for (int r = 0; r < 16; ++r) { p0[r] = 0.f; p1[r] = 0.f; }
;     const char* Ks = K_lds + cur * SHM_K;
; #pragma unroll
;     for (int d0 = 0; d0 < 12; ++d0) {
;       const int cb = (d0 * 16 + hi * 8) * 2;
;       const bf16x8 b0 = *(const bf16x8*)(Ks + r32 * KROW + cb);
;       const bf16x8 b1 = *(const bf16x8*)(Ks + (32 + r32) * KROW + cb);
;       p0 = __builtin_amdgcn_mfma_f32_32x32x16_bf16(b0, qr[d0], p0, 0, 0, 0);
;       p1 = __builtin_amdgcn_mfma_f32_32x32x16_bf16(b1, qr[d0], p1, 0, 0, 0);
;     }
;     float mn, alpha;
;     partialSM(p0, p1, m_reg, mn, alpha);
	s_mov_b32 s2, s34
	s_mov_b32 s3, s35
	s_mov_b32 vcc_lo, s34
	s_mov_b32 vcc_hi, s35
	s_add_u32 s2, s2, 0x31540000
	s_addc_u32 s3, s3, 0
	s_add_u32 vcc_lo, vcc_lo, 0x16518000
	s_addc_u32 vcc_hi, vcc_hi, 0
	v_lshl_add_u64 v[246:247], v[178:179], 0, s[2:3]
	global_load_dwordx4 v[146:149], v[246:247], off
	global_load_dwordx4 v[150:153], v[246:247], off offset:128
	v_lshl_add_u64 v[246:247], v[176:177], 0, vcc
	global_load_dwordx4 v[154:157], v[246:247], off offset:1280
	s_cmp_eq_u32 s101, 1
	s_cbranch_scc0 .Latt_pp_x0
	s_barrier
.Latt_pp_x0:
.LBB0_1260:
	v_lshl_add_u64 v[66:67], s[34:35], 0, v[178:179]
	v_add_co_u32_e32 v66, vcc, 0x31540000, v66
	s_mov_b32 s2, 0x31540000
	s_nop 0
	v_addc_co_u32_e32 v67, vcc, 0, v67, vcc
	v_lshl_add_u64 v[66:67], s[34:35], 0, v[176:177]
	v_add_co_u32_e32 v66, vcc, 0x16518000, v66
	s_and_b32 s42, s41, 1
	s_nop 0
	v_addc_co_u32_e32 v67, vcc, 0, v67, vcc
	v_lshl_add_u64 v[66:67], s[34:35], 0, v[174:175]
	v_add_co_u32_e32 v68, vcc, s2, v66
	s_mul_i32 s2, s42, 0x6400
	s_nop 0
	v_addc_co_u32_e32 v69, vcc, 0, v67, vcc
	v_add_co_u32_e32 v66, vcc, 0x31560000, v66
	v_add_u32_e32 v204, s2, v219
	s_nop 0
	v_addc_co_u32_e32 v67, vcc, 0, v67, vcc
	global_load_dwordx4 v[158:161], v[68:69], off offset:256
	global_load_dwordx4 v[162:165], v[66:67], off offset:256
	ds_read_b128 v[66:69], v204 offset:45568
	ds_read_b128 v[70:73], v204 offset:32768
	ds_read_b128 v[192:195], v204 offset:32800
	ds_read_b128 v[198:201], v204 offset:45600
	ds_read_b128 v[228:231], v204 offset:32832
	ds_read_b128 v[232:235], v204 offset:45632
	ds_read_b128 v[236:239], v204 offset:32864
	ds_read_b128 v[240:243], v204 offset:45664
	s_waitcnt vmcnt(16) lgkmcnt(6)
	v_mfma_f32_32x32x16_bf16 v[82:97], v[70:73], v[142:145], 0
	v_mfma_f32_32x32x16_bf16 v[66:81], v[66:69], v[142:145], 0
	s_waitcnt vmcnt(15) lgkmcnt(4)
	v_mfma_f32_32x32x16_bf16 v[82:97], v[192:195], v[138:141], v[82:97]
	v_mfma_f32_32x32x16_bf16 v[66:81], v[198:201], v[138:141], v[66:81]
	ds_read_b128 v[192:195], v204 offset:32896
	ds_read_b128 v[198:201], v204 offset:45696
	s_waitcnt vmcnt(14) lgkmcnt(4)
	v_mfma_f32_32x32x16_bf16 v[82:97], v[228:231], v[134:137], v[82:97]
	v_mfma_f32_32x32x16_bf16 v[66:81], v[232:235], v[134:137], v[66:81]
	ds_read_b128 v[228:231], v204 offset:32928
	ds_read_b128 v[232:235], v204 offset:45728
	s_waitcnt vmcnt(13) lgkmcnt(4)
	v_mfma_f32_32x32x16_bf16 v[82:97], v[236:239], v[130:133], v[82:97]
	v_mfma_f32_32x32x16_bf16 v[66:81], v[240:243], v[130:133], v[66:81]
	ds_read_b128 v[236:239], v204 offset:32960
	ds_read_b128 v[240:243], v204 offset:45760
	s_waitcnt vmcnt(12) lgkmcnt(4)
	v_mfma_f32_32x32x16_bf16 v[82:97], v[192:195], v[126:129], v[82:97]
	v_mfma_f32_32x32x16_bf16 v[66:81], v[198:201], v[126:129], v[66:81]
	ds_read_b128 v[192:195], v204 offset:32992
	ds_read_b128 v[198:201], v204 offset:45792
	s_waitcnt vmcnt(11) lgkmcnt(4)
	v_mfma_f32_32x32x16_bf16 v[82:97], v[228:231], v[122:125], v[82:97]
	v_mfma_f32_32x32x16_bf16 v[66:81], v[232:235], v[122:125], v[66:81]
	ds_read_b128 v[228:231], v204 offset:33024
	ds_read_b128 v[232:235], v204 offset:45824
	s_waitcnt vmcnt(10) lgkmcnt(4)
	v_mfma_f32_32x32x16_bf16 v[82:97], v[236:239], v[118:121], v[82:97]
	v_mfma_f32_32x32x16_bf16 v[66:81], v[240:243], v[118:121], v[66:81]
	ds_read_b128 v[236:239], v204 offset:33056
	ds_read_b128 v[240:243], v204 offset:45856
	s_waitcnt vmcnt(9) lgkmcnt(4)
	v_mfma_f32_32x32x16_bf16 v[82:97], v[192:195], v[114:117], v[82:97]
	v_mfma_f32_32x32x16_bf16 v[66:81], v[198:201], v[114:117], v[66:81]
	ds_read_b128 v[192:195], v204 offset:33088
	ds_read_b128 v[198:201], v204 offset:45888
	s_waitcnt vmcnt(8) lgkmcnt(4)
	v_mfma_f32_32x32x16_bf16 v[82:97], v[228:231], v[110:113], v[82:97]
	v_mfma_f32_32x32x16_bf16 v[66:81], v[232:235], v[110:113], v[66:81]
	ds_read_b128 v[228:231], v204 offset:33120
	ds_read_b128 v[232:235], v204 offset:45920
	s_waitcnt vmcnt(7) lgkmcnt(4)
	v_mfma_f32_32x32x16_bf16 v[82:97], v[236:239], v[106:109], v[82:97]
	v_mfma_f32_32x32x16_bf16 v[66:81], v[240:243], v[106:109], v[66:81]
	s_waitcnt vmcnt(6) lgkmcnt(2)
	v_mfma_f32_32x32x16_bf16 v[82:97], v[192:195], v[102:105], v[82:97]
	v_mfma_f32_32x32x16_bf16 v[66:81], v[198:201], v[102:105], v[66:81]
	s_waitcnt vmcnt(5) lgkmcnt(0)
	v_mfma_f32_32x32x16_bf16 v[82:97], v[228:231], v[98:101], v[82:97]
	v_mfma_f32_32x32x16_bf16 v[66:81], v[232:235], v[98:101], v[66:81]
	s_xor_b32 s2, s42, 1
	s_mul_i32 s3, s2, 0x6400
	v_add_u32_e32 v244, s3, v172
	s_waitcnt vmcnt(4)
	ds_write_b128 v244, v[146:149] offset:32768
	s_waitcnt vmcnt(3)
	ds_write_b128 v244, v[150:153] offset:32896
	s_waitcnt vmcnt(2)
	ds_write_b128 v244, v[154:157] offset:33024
	s_nop 9
	v_max_f32_e32 v192, v83, v83
	v_max_f32_e32 v193, v82, v82
	v_max_f32_e32 v192, v193, v192
	v_max3_f32 v192, v192, v84, v85
	v_max3_f32 v192, v192, v86, v87
	v_max3_f32 v192, v192, v88, v89
	v_max3_f32 v192, v192, v90, v91
	v_max3_f32 v192, v192, v92, v93
	v_max3_f32 v192, v192, v94, v95
	v_max3_f32 v192, v192, v96, v97
	v_max3_f32 v192, v192, v66, v67
	v_max3_f32 v192, v192, v68, v69
	v_max3_f32 v192, v192, v70, v71
	v_max3_f32 v192, v192, v72, v73
	v_max3_f32 v192, v192, v74, v75
	v_max3_f32 v192, v192, v76, v77
	v_max3_f32 v192, v192, v78, v79
	v_max3_f32 v192, v192, v80, v81
	v_mov_b32_e32 v193, v192
	s_nop 1
	v_permlane32_swap_b32_e32 v192, v193
	v_max_f32_e32 v193, v193, v193
	v_max_f32_e32 v192, v192, v192
	v_max_f32_e32 v192, v192, v193
	v_sub_f32_e32 v193, v192, v215
	v_cmp_ge_f32_e32 vcc, s90, v193
	v_max_f32_e32 v193, v215, v215
	v_max_f32_e32 v220, v193, v192
	v_sub_f32_e32 v192, v215, v220
	v_mul_f32_e32 v192, 0x3dd53b94, v192
	v_exp_f32_e32 v192, v192
	s_cmp_eq_u64 vcc, exec
	s_cselect_b64 s[12:13], -1, 0
	v_cndmask_b32_e64 v222, v192, 1.0, s[12:13]
	v_cmp_gt_f32_e32 vcc, 1.0, v222
	s_cbranch_vccz .LBB0_1264
; #define WAIT_L0() asm volatile("s_waitcnt lgkmcnt(0)" ::: "memory")
; DEVI int crow(int r, int hi) { return (r & 3) + 8 * (r >> 2) + 4 * hi; }
; DEVI void partialSM(f32x16& p0, f32x16& p1, float& m_reg, float& mn, float& alpha) {
;     ...
;   const float mnC = -mn * C;
; #pragma unroll
;   for (int r = 0; r < 16; ++r) p0[r] = __builtin_amdgcn_exp2f(fmaf(p0[r], C, mnC));
; #pragma unroll
;   for (int r = 0; r < 16; ++r) p1[r] = __builtin_amdgcn_exp2f(fmaf(p1[r], C, mnC));
; DEVI void attn_item(const u16* __restrict__ Qb, const u16* __restrict__ Kn, const u16* __restrict__ Kr, const u16* __restrict__ Vh, u16* __restrict__ Ob, int seq) {
;     ...
;     if (__any(alpha < 1.f)) {
;       if (hi == 0) al_l[r32] = alpha;
;       WAIT_L0();
; #pragma unroll
;       for (int d = 0; d < 4; ++d)
; #pragma unroll
;         for (int r = 0; r < 16; ++r) o[d][r] *= al_l[crow(r, hi)];
;     }
	s_and_saveexec_b64 s[2:3], s[10:11]
	ds_write_b32 v173, v222 offset:128
	s_or_b64 exec, exec, s[2:3]
	s_waitcnt lgkmcnt(0)
	v_add_u32_e32 v223, v171, v0
	ds_read_b128 v[192:195], v223 offset:224
	ds_read_b128 v[198:201], v223 offset:192
	ds_read_b128 v[204:207], v223 offset:160
	ds_read_b128 v[224:227], v223 offset:128
	s_waitcnt lgkmcnt(3)
	v_pk_mul_f32 v[14:15], v[14:15], v[192:193]
	s_waitcnt lgkmcnt(2)
	v_pk_mul_f32 v[10:11], v[10:11], v[198:199]
	s_waitcnt lgkmcnt(1)
	v_pk_mul_f32 v[6:7], v[6:7], v[204:205]
	v_pk_mul_f32 v[16:17], v[16:17], v[194:195]
	v_pk_mul_f32 v[12:13], v[12:13], v[200:201]
	v_pk_mul_f32 v[8:9], v[8:9], v[206:207]
	s_waitcnt lgkmcnt(0)
	v_pk_mul_f32 v[4:5], v[4:5], v[226:227]
	v_pk_mul_f32 v[2:3], v[2:3], v[224:225]
	v_pk_mul_f32 v[62:63], v[62:63], v[192:193]
	v_pk_mul_f32 v[58:59], v[58:59], v[198:199]
	v_pk_mul_f32 v[54:55], v[54:55], v[204:205]
	v_pk_mul_f32 v[64:65], v[64:65], v[194:195]
	v_pk_mul_f32 v[60:61], v[60:61], v[200:201]
	v_pk_mul_f32 v[56:57], v[56:57], v[206:207]
	v_pk_mul_f32 v[52:53], v[52:53], v[226:227]
	v_pk_mul_f32 v[50:51], v[50:51], v[224:225]
	v_pk_mul_f32 v[46:47], v[46:47], v[192:193]
	v_pk_mul_f32 v[42:43], v[42:43], v[198:199]
	v_pk_mul_f32 v[38:39], v[38:39], v[204:205]
	v_pk_mul_f32 v[48:49], v[48:49], v[194:195]
	v_pk_mul_f32 v[44:45], v[44:45], v[200:201]
	v_pk_mul_f32 v[40:41], v[40:41], v[206:207]
	v_pk_mul_f32 v[36:37], v[36:37], v[226:227]
	v_pk_mul_f32 v[34:35], v[34:35], v[224:225]
	v_pk_mul_f32 v[30:31], v[30:31], v[192:193]
	v_pk_mul_f32 v[26:27], v[26:27], v[198:199]
	v_pk_mul_f32 v[22:23], v[22:23], v[204:205]
	v_pk_mul_f32 v[32:33], v[32:33], v[194:195]
	v_pk_mul_f32 v[28:29], v[28:29], v[200:201]
	v_pk_mul_f32 v[24:25], v[24:25], v[206:207]
	v_pk_mul_f32 v[20:21], v[20:21], v[226:227]
	v_pk_mul_f32 v[18:19], v[18:19], v[224:225]
.LBB0_1264:
	s_waitcnt lgkmcnt(0)
	s_barrier
	s_add_i32 s2, s41, 1
	s_cmp_eq_u32 s2, s69
	s_cselect_b32 s2, 0, s96
	s_cselect_b32 s3, 0, s97
	s_cselect_b32 vcc_lo, 0, s78
	s_cselect_b32 vcc_hi, 0, s79
	s_add_u32 s2, s2, s34
	s_addc_u32 s3, s3, s35
	s_add_u32 vcc_lo, vcc_lo, s34
	s_addc_u32 vcc_hi, vcc_hi, s35
	s_add_u32 s2, s2, 0x31540000
	s_addc_u32 s3, s3, 0
	s_add_u32 vcc_lo, vcc_lo, 0x16518000
	s_addc_u32 vcc_hi, vcc_hi, 0
	v_lshl_add_u64 v[246:247], v[178:179], 0, s[2:3]
	global_load_dwordx4 v[146:149], v[246:247], off
	global_load_dwordx4 v[150:153], v[246:247], off offset:128
	v_lshl_add_u64 v[246:247], v[176:177], 0, vcc
	global_load_dwordx4 v[154:157], v[246:247], off offset:1280
	v_cndmask_b32_e64 v215, v220, v215, s[12:13]
	v_mul_f32_e32 v192, 0xbdd53b94, v215
	v_fmamk_f32 v66, v66, 0x3dd53b94, v192
	v_exp_f32_e32 v193, v66
	v_fmamk_f32 v66, v67, 0x3dd53b94, v192
	v_exp_f32_e32 v194, v66
	v_fmamk_f32 v66, v68, 0x3dd53b94, v192
	v_exp_f32_e32 v195, v66
	v_fmamk_f32 v66, v69, 0x3dd53b94, v192
	v_exp_f32_e32 v198, v66
	v_fmamk_f32 v66, v70, 0x3dd53b94, v192
	v_exp_f32_e32 v199, v66
	v_fmamk_f32 v66, v71, 0x3dd53b94, v192
	v_exp_f32_e32 v200, v66
	v_fmamk_f32 v66, v72, 0x3dd53b94, v192
	v_exp_f32_e32 v201, v66
	v_fmamk_f32 v66, v73, 0x3dd53b94, v192
	v_exp_f32_e32 v204, v66
	v_fmamk_f32 v66, v74, 0x3dd53b94, v192
	v_exp_f32_e32 v205, v66
	v_fmamk_f32 v66, v75, 0x3dd53b94, v192
	v_fmamk_f32 v82, v82, 0x3dd53b94, v192
	v_exp_f32_e32 v206, v66
	v_fmamk_f32 v66, v76, 0x3dd53b94, v192
	v_exp_f32_e32 v82, v82
	v_fmamk_f32 v83, v83, 0x3dd53b94, v192
	v_exp_f32_e32 v207, v66
	v_fmamk_f32 v66, v77, 0x3dd53b94, v192
	v_exp_f32_e32 v83, v83
	v_fmamk_f32 v84, v84, 0x3dd53b94, v192
	v_exp_f32_e32 v223, v66
	v_fmamk_f32 v66, v78, 0x3dd53b94, v192
	v_exp_f32_e32 v84, v84
	v_fmamk_f32 v85, v85, 0x3dd53b94, v192
	v_exp_f32_e32 v224, v66
	v_fmamk_f32 v66, v79, 0x3dd53b94, v192
	v_exp_f32_e32 v85, v85
	v_fmamk_f32 v86, v86, 0x3dd53b94, v192
	v_exp_f32_e32 v225, v66
	v_fmamk_f32 v66, v80, 0x3dd53b94, v192
	v_exp_f32_e32 v86, v86
	v_fmamk_f32 v87, v87, 0x3dd53b94, v192
	v_exp_f32_e32 v226, v66
	v_add_f32_e32 v66, 0, v82
	v_exp_f32_e32 v87, v87
	v_fmamk_f32 v88, v88, 0x3dd53b94, v192
	v_add_f32_e32 v66, v83, v66
	v_exp_f32_e32 v88, v88
	v_fmamk_f32 v89, v89, 0x3dd53b94, v192
	v_add_f32_e32 v66, v84, v66
	v_exp_f32_e32 v89, v89
	v_fmamk_f32 v90, v90, 0x3dd53b94, v192
	v_add_f32_e32 v66, v85, v66
	v_exp_f32_e32 v90, v90
	v_fmamk_f32 v91, v91, 0x3dd53b94, v192
	v_add_f32_e32 v66, v86, v66
	v_exp_f32_e32 v91, v91
	v_fmamk_f32 v92, v92, 0x3dd53b94, v192
	v_add_f32_e32 v66, v87, v66
	v_exp_f32_e32 v92, v92
	v_fmamk_f32 v93, v93, 0x3dd53b94, v192
	v_add_f32_e32 v66, v88, v66
	v_exp_f32_e32 v93, v93
	v_fmamk_f32 v94, v94, 0x3dd53b94, v192
	v_add_f32_e32 v66, v89, v66
	v_exp_f32_e32 v94, v94
	v_fmamk_f32 v95, v95, 0x3dd53b94, v192
	v_add_f32_e32 v66, v90, v66
	v_exp_f32_e32 v95, v95
	v_fmamk_f32 v96, v96, 0x3dd53b94, v192
	v_add_f32_e32 v66, v91, v66
	v_exp_f32_e32 v96, v96
	v_fmamk_f32 v97, v97, 0x3dd53b94, v192
	v_add_f32_e32 v66, v92, v66
	v_exp_f32_e32 v97, v97
	v_add_f32_e32 v66, v93, v66
	v_add_f32_e32 v66, v94, v66
	v_add_f32_e32 v66, v95, v66
	v_add_f32_e32 v66, v96, v66
	v_add_f32_e32 v66, v97, v66
	v_add_f32_e32 v66, v193, v66
	v_add_f32_e32 v66, v194, v66
	v_add_f32_e32 v66, v195, v66
	v_add_f32_e32 v66, v198, v66
	v_add_f32_e32 v66, v199, v66
	v_add_f32_e32 v66, v200, v66
	v_add_f32_e32 v66, v201, v66
	v_add_f32_e32 v66, v204, v66
	v_add_f32_e32 v66, v205, v66
	v_add_f32_e32 v66, v206, v66
	v_fmac_f32_e32 v192, 0x3dd53b94, v81
	v_add_f32_e32 v66, v207, v66
	v_exp_f32_e32 v81, v192
	v_add_f32_e32 v66, v223, v66
	v_add_f32_e32 v66, v224, v66
	v_add_f32_e32 v66, v225, v66
	v_add_f32_e32 v66, v226, v66
	v_add_f32_e32 v66, v81, v66
	v_mov_b32_e32 v67, v66
; #define WAIT_L0() asm volatile("s_waitcnt lgkmcnt(0)" ::: "memory")
; #define SBAR() __builtin_amdgcn_sched_barrier(0)
; DEVI void finishSM(f32x16& p0, f32x16& p1, float alpha, float& l_reg, bf16x8& pa0, bf16x8& pa1, bf16x8& pa2, bf16x8& pa3) {
;     ...
;   { auto rr = __builtin_amdgcn_permlane32_swap(__float_as_uint(ps), __float_as_uint(ps), false, false);
;     ps = __uint_as_float(rr[0]) + __uint_as_float(rr[1]); }
;   l_reg = l_reg * alpha + ps;
;     ...
;   PK4(p0, 0, pa0); PK4(p0, 8, pa1); PK4(p1, 0, pa2); PK4(p1, 8, pa3);
;     ...
; }
; DEVI int v_st(int k, int c) { const int kk = (k & ~0xC) | ((k & 4) << 1) | ((k & 8) >> 1); return ((kk >> 3) * 4 + (c >> 5)) * 512 + ((kk & 7) * 32 + (c & 31)) * 2; }
; DEVI int v_rd_base(int lane) { return ((lane & 3) << 3) | (((lane >> 2) & 3) << 6) | (((lane >> 4) & 1) << 5) | (((lane >> 5) & 1) << 8); }
; template <int OFF> DEVI s16x4 tr_read(int vb) {
;   s16x4 r; asm volatile("ds_read_b64_tr_b16 %0, %1 offset:%2" : "=&v"(r) : "v"(vb), "i"(OFF) : "memory"); return r;
; }
; template <int D0> DEVI void pv_one(f32x16& od, int vb, bf16x8 pa0, bf16x8 pa1, bf16x8 pa2, bf16x8 pa3) {
;   const s16x4 l0 = tr_read<v_rd_off(D0, 0, 0)>(vb), h0 = tr_read<v_rd_off(D0, 0, 1)>(vb), l1 = tr_read<v_rd_off(D0, 1, 0)>(vb), h1 = tr_read<v_rd_off(D0, 1, 1)>(vb);
;   const s16x4 l2 = tr_read<v_rd_off(D0, 2, 0)>(vb), h2 = tr_read<v_rd_off(D0, 2, 1)>(vb), l3 = tr_read<v_rd_off(D0, 3, 0)>(vb), h3 = tr_read<v_rd_off(D0, 3, 1)>(vb);
;   WAIT_L0(); SBAR();
;     ...
;   od = __builtin_amdgcn_mfma_f32_32x32x16_bf16(pa0, PK(l0, h0), od, 0, 0, 0);
;   od = __builtin_amdgcn_mfma_f32_32x32x16_bf16(pa1, PK(l1, h1), od, 0, 0, 0);
;   od = __builtin_amdgcn_mfma_f32_32x32x16_bf16(pa2, PK(l2, h2), od, 0, 0, 0);
;   od = __builtin_amdgcn_mfma_f32_32x32x16_bf16(pa3, PK(l3, h3), od, 0, 0, 0);
;     ...
; }
; DEVI void pv_pipe(f32x16* o, int vb, bf16x8 pa0, bf16x8 pa1, bf16x8 pa2, bf16x8 pa3) {
;   s16x4 a[8], b[8];
;   TR8(0, a); TR8(1, b);
;   asm volatile("s_waitcnt lgkmcnt(8)" ::: "memory"); SBAR();
;   MM4(o[0], a); SBAR();
;   TR8(2, a);
;   asm volatile("s_waitcnt lgkmcnt(8)" ::: "memory"); SBAR();
;   MM4(o[1], b); SBAR();
;   TR8(3, b);
;   asm volatile("s_waitcnt lgkmcnt(8)" ::: "memory"); SBAR();
;   MM4(o[2], a); SBAR();
;   asm volatile("s_waitcnt lgkmcnt(0)" ::: "memory"); SBAR();
;   MM4(o[3], b);
; }
	s_nop 1
	v_permlane32_swap_b32_e32 v66, v67
	v_add_f32_e32 v220, v66, v67
	s_add_i32 s41, s41, 1
	v_fmac_f32_e32 v220, v221, v222
	v_cvt_pk_bf16_f32 v66, v82, v83
	v_cvt_pk_bf16_f32 v67, v84, v85
	v_cvt_pk_bf16_f32 v68, v86, v87
	v_cvt_pk_bf16_f32 v69, v88, v89
	v_cvt_pk_bf16_f32 v70, v90, v91
	v_cvt_pk_bf16_f32 v71, v92, v93
	v_cvt_pk_bf16_f32 v72, v94, v95
	v_cvt_pk_bf16_f32 v73, v96, v97
	v_cvt_pk_bf16_f32 v74, v193, v194
	v_cvt_pk_bf16_f32 v75, v195, v198
	v_cvt_pk_bf16_f32 v76, v199, v200
	v_cvt_pk_bf16_f32 v77, v201, v204
	v_cvt_pk_bf16_f32 v78, v205, v206
	v_cvt_pk_bf16_f32 v79, v207, v223
	v_cvt_pk_bf16_f32 v80, v224, v225
	v_cvt_pk_bf16_f32 v81, v226, v81
	v_permlane32_swap_b32_e32 v66, v68
	v_permlane32_swap_b32_e32 v67, v69
	v_permlane32_swap_b32_e32 v70, v72
	v_permlane32_swap_b32_e32 v71, v73
	v_permlane32_swap_b32_e32 v74, v76
	v_permlane32_swap_b32_e32 v75, v77
	v_permlane32_swap_b32_e32 v78, v80
	v_permlane32_swap_b32_e32 v79, v81
	v_lshl_or_b32 v221, s42, 14, v214
	ds_read_b64_tr_b16 v[82:83], v221 offset:0
	ds_read_b64_tr_b16 v[84:85], v221 offset:0x800
	ds_read_b64_tr_b16 v[86:87], v221 offset:0x1000
	ds_read_b64_tr_b16 v[88:89], v221 offset:0x1800
	ds_read_b64_tr_b16 v[90:91], v221 offset:0x2000
	ds_read_b64_tr_b16 v[92:93], v221 offset:0x2800
	ds_read_b64_tr_b16 v[94:95], v221 offset:0x3000
	ds_read_b64_tr_b16 v[96:97], v221 offset:0x3800
	ds_read_b64_tr_b16 v[192:193], v221 offset:0x200
	ds_read_b64_tr_b16 v[194:195], v221 offset:0xa00
	ds_read_b64_tr_b16 v[198:199], v221 offset:0x1200
	ds_read_b64_tr_b16 v[200:201], v221 offset:0x1a00
	ds_read_b64_tr_b16 v[204:205], v221 offset:0x2200
	ds_read_b64_tr_b16 v[206:207], v221 offset:0x2a00
	ds_read_b64_tr_b16 v[222:223], v221 offset:0x3200
	ds_read_b64_tr_b16 v[224:225], v221 offset:0x3a00
	s_waitcnt lgkmcnt(8)
	s_nop 0
	v_mfma_f32_32x32x16_bf16 v[2:17], v[66:69], v[82:85], v[2:17]
	v_mfma_f32_32x32x16_bf16 v[2:17], v[70:73], v[86:89], v[2:17]
	v_mfma_f32_32x32x16_bf16 v[2:17], v[74:77], v[90:93], v[2:17]
	v_mfma_f32_32x32x16_bf16 v[2:17], v[78:81], v[94:97], v[2:17]
	ds_read_b64_tr_b16 v[82:83], v221 offset:0x400
	ds_read_b64_tr_b16 v[84:85], v221 offset:0xc00
	ds_read_b64_tr_b16 v[86:87], v221 offset:0x1400
	ds_read_b64_tr_b16 v[88:89], v221 offset:0x1c00
	ds_read_b64_tr_b16 v[90:91], v221 offset:0x2400
	ds_read_b64_tr_b16 v[92:93], v221 offset:0x2c00
	ds_read_b64_tr_b16 v[94:95], v221 offset:0x3400
	ds_read_b64_tr_b16 v[96:97], v221 offset:0x3c00
	s_waitcnt lgkmcnt(8)
	v_mfma_f32_32x32x16_bf16 v[50:65], v[66:69], v[192:195], v[50:65]
	v_mfma_f32_32x32x16_bf16 v[50:65], v[70:73], v[198:201], v[50:65]
	v_mfma_f32_32x32x16_bf16 v[50:65], v[74:77], v[204:207], v[50:65]
	v_mfma_f32_32x32x16_bf16 v[50:65], v[78:81], v[222:225], v[50:65]
	ds_read_b64_tr_b16 v[192:193], v221 offset:0x600
	ds_read_b64_tr_b16 v[194:195], v221 offset:0xe00
	ds_read_b64_tr_b16 v[198:199], v221 offset:0x1600
	ds_read_b64_tr_b16 v[200:201], v221 offset:0x1e00
	ds_read_b64_tr_b16 v[204:205], v221 offset:0x2600
	ds_read_b64_tr_b16 v[206:207], v221 offset:0x2e00
	ds_read_b64_tr_b16 v[222:223], v221 offset:0x3600
	ds_read_b64_tr_b16 v[224:225], v221 offset:0x3e00
	s_waitcnt lgkmcnt(8)
	v_mfma_f32_32x32x16_bf16 v[34:49], v[66:69], v[82:85], v[34:49]
	v_mfma_f32_32x32x16_bf16 v[34:49], v[70:73], v[86:89], v[34:49]
	v_mfma_f32_32x32x16_bf16 v[34:49], v[74:77], v[90:93], v[34:49]
	v_mfma_f32_32x32x16_bf16 v[34:49], v[78:81], v[94:97], v[34:49]
	s_waitcnt lgkmcnt(0)
	v_mfma_f32_32x32x16_bf16 v[18:33], v[66:69], v[192:195], v[18:33]
	s_xor_b32 s2, s42, 1
	s_nop 0
	s_mul_i32 s3, s2, 0x6400
	s_lshl_b32 s2, s2, 14
	v_add_u32_e32 v66, s2, v216
	v_mfma_f32_32x32x16_bf16 v[18:33], v[70:73], v[198:201], v[18:33]
	v_add_u32_e32 v67, s2, v217
	v_lshl_add_u64 v[174:175], v[174:175], 0, s[96:97]
	v_lshl_add_u64 v[176:177], v[176:177], 0, s[78:79]
	v_lshl_add_u64 v[178:179], v[178:179], 0, s[96:97]
	s_cmp_eq_u32 s69, s41
	s_waitcnt vmcnt(4)
	ds_write_b128 v66, v[158:161]
	s_waitcnt vmcnt(3)
	ds_write_b128 v67, v[162:165]
	v_mfma_f32_32x32x16_bf16 v[18:33], v[74:77], v[204:207], v[18:33]
	s_waitcnt lgkmcnt(0)
	s_barrier
	v_mfma_f32_32x32x16_bf16 v[18:33], v[78:81], v[222:225], v[18:33]
	s_cbranch_scc1 .LBB0_1266
	v_mov_b32_e32 v221, v220
	s_branch .LBB0_1260
; #define WAIT_L0() asm volatile("s_waitcnt lgkmcnt(0)" ::: "memory")
; DEVI int crow(int r, int hi) { return (r & 3) + 8 * (r >> 2) + 4 * hi; }
; DEVI void partialSM(f32x16& p0, f32x16& p1, float& m_reg, float& mn, float& alpha) {
;     ...
;   float pmax = p0[0];
; #pragma unroll
;   for (int r = 1; r < 16; ++r) pmax = fmaxf(pmax, p0[r]);
; #pragma unroll
;   for (int r = 0; r < 16; ++r) pmax = fmaxf(pmax, p1[r]);
;   { auto rr = __builtin_amdgcn_permlane32_swap(__float_as_uint(pmax), __float_as_uint(pmax), false, false);
;     pmax = fmaxf(__uint_as_float(rr[0]), __uint_as_float(rr[1])); }
;   if (__builtin_expect(__all(pmax - m_reg <= THR / MLA_SCALE), 1)) { mn = m_reg; alpha = 1.f; }
;   else { mn = fmaxf(m_reg, pmax); alpha = __builtin_amdgcn_exp2f((m_reg - mn) * C); m_reg = mn; }
; DEVI void attn_item(const u16* __restrict__ Qb, const u16* __restrict__ Kn, const u16* __restrict__ Kr, const u16* __restrict__ Vh, u16* __restrict__ Ob, int seq) {
;     ...
; #pragma unroll
;     for (int d0 = 0; d0 < 12; ++d0) {
;       const int cb = (d0 * 16 + hi * 8) * 2;
;       const bf16x8 b0 = *(const bf16x8*)(Ks + r32 * KROW + cb);
;       const bf16x8 b1 = *(const bf16x8*)(Ks + (32 + r32) * KROW + cb);
;       p0 = __builtin_amdgcn_mfma_f32_32x32x16_bf16(b0, qr[d0], p0, 0, 0, 0);
;       p1 = __builtin_amdgcn_mfma_f32_32x32x16_bf16(b1, qr[d0], p1, 0, 0, 0);
;     }
;     float mn, alpha;
;     partialSM(p0, p1, m_reg, mn, alpha);
;     if (__any(alpha < 1.f)) {
;       if (hi == 0) al_l[r32] = alpha;
;       WAIT_L0();
; #pragma unroll
;       for (int d = 0; d < 4; ++d)
; #pragma unroll
;         for (int r = 0; r < 16; ++r) o[d][r] *= al_l[crow(r, hi)];
;     }
.LBB0_1266:
	s_waitcnt vmcnt(0)
	s_and_b32 s41, s69, 1
	s_mul_i32 s2, s41, 0x6400
	v_add3_u32 v146, v218, s2, v0
	ds_read_b128 v[66:69], v146 offset:32768
	s_waitcnt lgkmcnt(0)
	v_mfma_f32_32x32x16_bf16 v[82:97], v[66:69], v[142:145], 0
	ds_read_b128 v[66:69], v146 offset:45568
	s_waitcnt lgkmcnt(0)
	v_mfma_f32_32x32x16_bf16 v[66:81], v[66:69], v[142:145], 0
	ds_read_b128 v[142:145], v146 offset:32800
	s_waitcnt lgkmcnt(0)
	v_mfma_f32_32x32x16_bf16 v[82:97], v[142:145], v[138:141], v[82:97]
	ds_read_b128 v[142:145], v146 offset:45600
	s_waitcnt lgkmcnt(0)
	v_mfma_f32_32x32x16_bf16 v[66:81], v[142:145], v[138:141], v[66:81]
	ds_read_b128 v[138:141], v146 offset:32832
	s_waitcnt lgkmcnt(0)
	v_mfma_f32_32x32x16_bf16 v[82:97], v[138:141], v[134:137], v[82:97]
	ds_read_b128 v[138:141], v146 offset:45632
	s_waitcnt lgkmcnt(0)
	v_mfma_f32_32x32x16_bf16 v[66:81], v[138:141], v[134:137], v[66:81]
	ds_read_b128 v[134:137], v146 offset:32864
	s_waitcnt lgkmcnt(0)
	v_mfma_f32_32x32x16_bf16 v[82:97], v[134:137], v[130:133], v[82:97]
	ds_read_b128 v[134:137], v146 offset:45664
	s_waitcnt lgkmcnt(0)
	v_mfma_f32_32x32x16_bf16 v[66:81], v[134:137], v[130:133], v[66:81]
	ds_read_b128 v[130:133], v146 offset:32896
	s_waitcnt lgkmcnt(0)
	v_mfma_f32_32x32x16_bf16 v[82:97], v[130:133], v[126:129], v[82:97]
	ds_read_b128 v[130:133], v146 offset:45696
	s_waitcnt lgkmcnt(0)
	v_mfma_f32_32x32x16_bf16 v[66:81], v[130:133], v[126:129], v[66:81]
	ds_read_b128 v[126:129], v146 offset:32928
	s_waitcnt lgkmcnt(0)
	v_mfma_f32_32x32x16_bf16 v[82:97], v[126:129], v[122:125], v[82:97]
	ds_read_b128 v[126:129], v146 offset:45728
	s_waitcnt lgkmcnt(0)
	v_mfma_f32_32x32x16_bf16 v[66:81], v[126:129], v[122:125], v[66:81]
	ds_read_b128 v[122:125], v146 offset:32960
	s_waitcnt lgkmcnt(0)
	v_mfma_f32_32x32x16_bf16 v[82:97], v[122:125], v[118:121], v[82:97]
	ds_read_b128 v[122:125], v146 offset:45760
	s_waitcnt lgkmcnt(0)
	v_mfma_f32_32x32x16_bf16 v[66:81], v[122:125], v[118:121], v[66:81]
	ds_read_b128 v[118:121], v146 offset:32992
	s_waitcnt lgkmcnt(0)
	v_mfma_f32_32x32x16_bf16 v[82:97], v[118:121], v[114:117], v[82:97]
	ds_read_b128 v[118:121], v146 offset:45792
	s_waitcnt lgkmcnt(0)
	v_mfma_f32_32x32x16_bf16 v[66:81], v[118:121], v[114:117], v[66:81]
	ds_read_b128 v[114:117], v146 offset:33024
	s_waitcnt lgkmcnt(0)
	v_mfma_f32_32x32x16_bf16 v[82:97], v[114:117], v[110:113], v[82:97]
	ds_read_b128 v[114:117], v146 offset:45824
	s_waitcnt lgkmcnt(0)
	v_mfma_f32_32x32x16_bf16 v[66:81], v[114:117], v[110:113], v[66:81]
	ds_read_b128 v[110:113], v146 offset:33056
	s_waitcnt lgkmcnt(0)
	v_mfma_f32_32x32x16_bf16 v[82:97], v[110:113], v[106:109], v[82:97]
	ds_read_b128 v[110:113], v146 offset:45856
	s_waitcnt lgkmcnt(0)
	v_mfma_f32_32x32x16_bf16 v[66:81], v[110:113], v[106:109], v[66:81]
	ds_read_b128 v[106:109], v146 offset:33088
	s_waitcnt lgkmcnt(0)
	v_mfma_f32_32x32x16_bf16 v[82:97], v[106:109], v[102:105], v[82:97]
	ds_read_b128 v[106:109], v146 offset:33120
	s_waitcnt lgkmcnt(0)
	v_mfma_f32_32x32x16_bf16 v[82:97], v[106:109], v[98:101], v[82:97]
	ds_read_b128 v[106:109], v146 offset:45888
	ds_read_b128 v[110:113], v146 offset:45920
	s_waitcnt lgkmcnt(1)
	v_mfma_f32_32x32x16_bf16 v[66:81], v[106:109], v[102:105], v[66:81]
	s_nop 7
	v_max_f32_e32 v114, v83, v83
	v_max_f32_e32 v115, v82, v82
	v_max_f32_e32 v114, v115, v114
	v_max3_f32 v102, v114, v84, v85
	v_max3_f32 v102, v102, v86, v87
	v_max3_f32 v102, v102, v88, v89
	v_max3_f32 v102, v102, v90, v91
	s_waitcnt lgkmcnt(0)
	v_mfma_f32_32x32x16_bf16 v[66:81], v[110:113], v[98:101], v[66:81]
	v_max3_f32 v102, v102, v92, v93
	v_max3_f32 v102, v102, v94, v95
	v_max3_f32 v102, v102, v96, v97
	s_nop 8
	v_max3_f32 v98, v102, v66, v67
	v_max3_f32 v98, v98, v68, v69
	v_max3_f32 v98, v98, v70, v71
	v_max3_f32 v98, v98, v72, v73
	v_max3_f32 v98, v98, v74, v75
	v_max3_f32 v98, v98, v76, v77
	v_max3_f32 v98, v98, v78, v79
	v_max3_f32 v98, v98, v80, v81
	v_mov_b32_e32 v99, v98
	s_nop 1
	v_permlane32_swap_b32_e32 v98, v99
	v_max_f32_e32 v99, v99, v99
	v_max_f32_e32 v98, v98, v98
	v_max_f32_e32 v98, v98, v99
	v_max_f32_e32 v99, v215, v215
	v_max_f32_e32 v99, v99, v98
	v_sub_f32_e32 v100, v98, v215
	v_sub_f32_e32 v98, v215, v99
	v_mul_f32_e32 v98, 0x3dd53b94, v98
	v_exp_f32_e32 v98, v98
	v_cmp_ge_f32_e32 vcc, s90, v100
	s_cmp_eq_u64 vcc, exec
	s_cselect_b64 s[12:13], -1, 0
	v_cndmask_b32_e64 v98, v98, 1.0, s[12:13]
	v_cmp_gt_f32_e32 vcc, 1.0, v98
	s_cbranch_vccz .LBB0_1270
	s_and_saveexec_b64 s[2:3], s[10:11]
	ds_write_b32 v173, v98 offset:128
	s_or_b64 exec, exec, s[2:3]
	s_waitcnt lgkmcnt(0)
	v_add_u32_e32 v112, v171, v0
	ds_read_b128 v[100:103], v112 offset:224
	ds_read_b128 v[104:107], v112 offset:192
	ds_read_b128 v[108:111], v112 offset:160
	ds_read_b128 v[112:115], v112 offset:128
	s_waitcnt lgkmcnt(3)
	v_pk_mul_f32 v[14:15], v[14:15], v[100:101]
	s_waitcnt lgkmcnt(2)
	v_pk_mul_f32 v[10:11], v[10:11], v[104:105]
	s_waitcnt lgkmcnt(1)
	v_pk_mul_f32 v[6:7], v[6:7], v[108:109]
	v_pk_mul_f32 v[16:17], v[16:17], v[102:103]
	v_pk_mul_f32 v[12:13], v[12:13], v[106:107]
	v_pk_mul_f32 v[8:9], v[8:9], v[110:111]
	s_waitcnt lgkmcnt(0)
	v_pk_mul_f32 v[4:5], v[4:5], v[114:115]
	v_pk_mul_f32 v[2:3], v[2:3], v[112:113]
	v_pk_mul_f32 v[62:63], v[62:63], v[100:101]
	v_pk_mul_f32 v[58:59], v[58:59], v[104:105]
	v_pk_mul_f32 v[54:55], v[54:55], v[108:109]
	v_pk_mul_f32 v[64:65], v[64:65], v[102:103]
	v_pk_mul_f32 v[60:61], v[60:61], v[106:107]
	v_pk_mul_f32 v[56:57], v[56:57], v[110:111]
	v_pk_mul_f32 v[52:53], v[52:53], v[114:115]
	v_pk_mul_f32 v[50:51], v[50:51], v[112:113]
	v_pk_mul_f32 v[46:47], v[46:47], v[100:101]
	v_pk_mul_f32 v[42:43], v[42:43], v[104:105]
	v_pk_mul_f32 v[38:39], v[38:39], v[108:109]
	v_pk_mul_f32 v[48:49], v[48:49], v[102:103]
	v_pk_mul_f32 v[44:45], v[44:45], v[106:107]
	v_pk_mul_f32 v[40:41], v[40:41], v[110:111]
	v_pk_mul_f32 v[36:37], v[36:37], v[114:115]
	v_pk_mul_f32 v[34:35], v[34:35], v[112:113]
	v_pk_mul_f32 v[30:31], v[30:31], v[100:101]
	v_pk_mul_f32 v[26:27], v[26:27], v[104:105]
	v_pk_mul_f32 v[22:23], v[22:23], v[108:109]
	v_pk_mul_f32 v[32:33], v[32:33], v[102:103]
	v_pk_mul_f32 v[28:29], v[28:29], v[106:107]
	v_pk_mul_f32 v[24:25], v[24:25], v[110:111]
	v_pk_mul_f32 v[20:21], v[20:21], v[114:115]
	v_pk_mul_f32 v[18:19], v[18:19], v[112:113]
